# cooperative DSA indexer: 4 waves of a block split key groups, 2 queries per MFMA (rows 0-7/8-15), scores exchanged through LDS, plus hand-written top-k select
# speedup vs baseline: 1.0267x; 1.0267x over previous
.LBB0_597:
	s_lshl_b32 s0, s78, 2
	s_add_i32 s0, s0, 0x7fffff00
	s_and_b32 s0, s0, 0x7ffffffc
	v_readlane_b32 s4, v250, 12
	s_xor_b32 s0, s0, 0xffc
	v_readlane_b32 s1, v250, 23
	v_mov_b32_e32 v80, v196
	v_readlane_b32 s5, v250, 13
	s_add_i32 s10, s0, s1
	s_load_dwordx4 s[0:3], s[4:5], 0x168
	s_ashr_i32 s11, s10, 31
	s_bfe_u32 s50, s10, 0x60006
	s_lshl_b64 s[6:7], s[10:11], 9
	v_and_b32_e32 v81, 15, v80
	s_waitcnt lgkmcnt(0)
	s_add_u32 s0, s0, s6
	s_addc_u32 s1, s1, s7
	s_and_b32 s33, s10, 0xfffff000
	s_load_dwordx2 s[4:5], s[4:5], 0x178
	v_or_b32_e32 v10, s33, v81
	v_lshlrev_b32_e32 v0, 6, v80
	v_ashrrev_i32_e32 v11, 31, v10
	v_and_b32_e32 v0, 0x1c0, v0
	v_lshlrev_b64 v[10:11], 6, v[10:11]
	v_lshl_add_u64 v[2:3], s[0:1], 0, v[0:1]
	v_and_b32_e32 v0, 48, v80
	s_add_i32 s6, s50, 2
	v_lshl_add_u64 v[10:11], s[2:3], 0, v[10:11]
	s_lshr_b32 s8, s6, 1
	v_writelane_b32 v252, s10, 36
	s_lshl_b64 s[0:1], s[10:11], 5
	s_waitcnt vmcnt(3)
	v_lshl_add_u64 v[70:71], v[10:11], 0, v[0:1]
	s_waitcnt lgkmcnt(0)
	s_add_u32 s0, s4, s0
	v_add_co_u32_e32 v10, vcc, s70, v70
	v_lshl_add_u64 v[2:3], v[2:3], 0, v[0:1]
	s_addc_u32 s1, s5, s1
	v_and_b32_e32 v6, 16, v80
	v_addc_co_u32_e32 v11, vcc, 0, v71, vcc
	s_lshl_b32 s6, s6, 12
	s_nop 0
	v_writelane_b32 v252, s11, 37
	v_cmp_lt_i32_e32 vcc, v132, v180
	v_and_b32_e32 v207, 63, v80
	v_readlane_b32 s7, v250, 34
	v_bfe_u32 v10, v80, 4, 2
	v_readlane_b32 s4, v250, 12
	v_cndmask_b32_e32 v0, v178, v132, vcc
	v_readlane_b32 s5, v250, 13
	v_lshl_add_u32 v85, v207, 2, s7
	v_lshlrev_b32_e32 v206, 2, v0
	v_lshlrev_b32_e32 v0, 3, v10
	v_cmp_gt_u32_e64 s[42:43], 16, v207
	s_load_dwordx4 s[0:3], s[4:5], 0x168
	s_load_dwordx2 s[4:5], s[4:5], 0x178
	s_and_b32 s12, s10, 3
	s_andn2_b32 s13, s10, 3
	v_lshlrev_b32_e32 v70, 4, v10
	v_lshrrev_b32_e32 v71, 3, v81
	v_and_b32_e32 v72, 7, v81
	v_lshl_add_u32 v73, v71, 9, v70
	v_lshl_add_u32 v73, v72, 6, v73
	v_and_b32_e32 v71, 1, v10
	v_lshrrev_b32_e32 v72, 1, v10
	v_lshl_or_b32 v71, v71, 1, v72
	v_mul_u32_u24_e32 v71, 0x4500, v71
	s_lshl_b32 s6, s12, 4
	v_add_u32_e32 v72, s6, v81
	v_lshl_add_u32 v78, v72, 2, v71
	v_add_u32_e32 v72, s33, v72
	v_mov_b32_e32 v75, 0
	v_lshl_add_u32 v74, v72, 6, v70
	s_waitcnt lgkmcnt(0)
	v_lshl_add_u64 v[74:75], s[2:3], 0, v[74:75]
	s_mov_b64 s[14:15], 0x1000
	s_lshl_b32 s6, s13, 9
	s_add_u32 s0, s0, s6
	s_addc_u32 s1, s1, 0
	s_lshl_b32 s6, s13, 5
	s_add_u32 s4, s4, s6
	s_addc_u32 s5, s5, 0
	global_load_dwordx4 v[10:13], v73, s[0:1]
	global_load_dwordx4 v[14:17], v73, s[0:1] offset:1024
	global_load_dwordx4 v[6:9], v70, s[4:5]
	global_load_dwordx4 v[2:5], v70, s[4:5] offset:64
	s_add_i32 s8, s50, 4
	s_lshr_b32 s8, s8, 2
	s_mov_b32 s9, 0
	s_mov_b32 s6, 0x3e3504f3
	global_load_dwordx4 v[18:21], v[74:75], off
	v_lshl_add_u64 v[74:75], v[74:75], 0, s[14:15]
	global_load_dwordx4 v[22:25], v[74:75], off
	v_lshl_add_u64 v[74:75], v[74:75], 0, s[14:15]
	global_load_dwordx4 v[26:29], v[74:75], off
	v_lshl_add_u64 v[74:75], v[74:75], 0, s[14:15]
	global_load_dwordx4 v[30:33], v[74:75], off
	v_lshl_add_u64 v[74:75], v[74:75], 0, s[14:15]
	s_waitcnt vmcnt(4)
	v_mul_f32_e32 v6, s6, v6
	v_mul_f32_e32 v7, s6, v7
	v_mul_f32_e32 v8, s6, v8
	v_mul_f32_e32 v9, s6, v9
	v_mul_f32_e32 v2, s6, v2
	v_mul_f32_e32 v3, s6, v3
	v_mul_f32_e32 v4, s6, v4
	v_mul_f32_e32 v5, s6, v5
	s_cmp_lt_u32 s8, 2
	s_cbranch_scc1 .Lidx_loopX
	global_load_dwordx4 v[34:37], v[74:75], off
	v_lshl_add_u64 v[74:75], v[74:75], 0, s[14:15]
	global_load_dwordx4 v[38:41], v[74:75], off
	v_lshl_add_u64 v[74:75], v[74:75], 0, s[14:15]
	global_load_dwordx4 v[42:45], v[74:75], off
	v_lshl_add_u64 v[74:75], v[74:75], 0, s[14:15]
	global_load_dwordx4 v[46:49], v[74:75], off
	v_lshl_add_u64 v[74:75], v[74:75], 0, s[14:15]
.Lidx_loopX:
	s_add_i32 s10, s9, 1
	s_cmp_lt_u32 s10, s8
	s_cbranch_scc1 .Lidx_wX4
	s_waitcnt vmcnt(0)
	s_branch .Lidx_cX
.Lidx_wX4:
	s_waitcnt vmcnt(4)
.Lidx_cX:
	v_mfma_f32_16x16x32_bf16 v[50:53], v[10:13], v[18:21], 0
	v_mfma_f32_16x16x32_bf16 v[54:57], v[14:17], v[18:21], 0
	v_mfma_f32_16x16x32_bf16 v[58:61], v[10:13], v[22:25], 0
	v_mfma_f32_16x16x32_bf16 v[62:65], v[14:17], v[22:25], 0
	v_mfma_f32_16x16x32_bf16 v[86:89], v[10:13], v[26:29], 0
	v_mfma_f32_16x16x32_bf16 v[90:93], v[14:17], v[26:29], 0
	v_mfma_f32_16x16x32_bf16 v[94:97], v[10:13], v[30:33], 0
	v_mfma_f32_16x16x32_bf16 v[98:101], v[14:17], v[30:33], 0
	s_add_i32 s10, s9, 2
	s_cmp_lt_u32 s10, s8
	s_cbranch_scc0 .Lidx_nlX
	global_load_dwordx4 v[18:21], v[74:75], off
	v_lshl_add_u64 v[74:75], v[74:75], 0, s[14:15]
	global_load_dwordx4 v[22:25], v[74:75], off
	v_lshl_add_u64 v[74:75], v[74:75], 0, s[14:15]
	global_load_dwordx4 v[26:29], v[74:75], off
	v_lshl_add_u64 v[74:75], v[74:75], 0, s[14:15]
	global_load_dwordx4 v[30:33], v[74:75], off
	v_lshl_add_u64 v[74:75], v[74:75], 0, s[14:15]
.Lidx_nlX:
	s_nop 1
	v_med3_f32 v70, v50, 0, v201
	v_med3_f32 v71, v51, 0, v201
	v_med3_f32 v72, v52, 0, v201
	v_med3_f32 v73, v53, 0, v201
	v_mul_f32_e32 v66, v70, v6
	v_fma_f32 v66, v71, v7, v66
	v_fma_f32 v66, v72, v8, v66
	v_fma_f32 v66, v73, v9, v66
	v_med3_f32 v70, v54, 0, v201
	v_med3_f32 v71, v55, 0, v201
	v_med3_f32 v72, v56, 0, v201
	v_med3_f32 v73, v57, 0, v201
	v_mul_f32_e32 v67, v70, v2
	v_fma_f32 v67, v71, v3, v67
	v_fma_f32 v67, v72, v4, v67
	v_fma_f32 v67, v73, v5, v67
	s_nop 1
	v_permlane16_swap_b32 v66, v67
	s_nop 0
	v_add_f32_e32 v68, v66, v67
	v_add_f32_e32 v68, 0, v68
	v_ashrrev_i32_e32 v69, 31, v68
	v_or_b32_e32 v69, 0x80000000, v69
	v_xor_b32_e32 v68, v68, v69
	ds_write_b32 v78, v68
	v_med3_f32 v70, v58, 0, v201
	v_med3_f32 v71, v59, 0, v201
	v_med3_f32 v72, v60, 0, v201
	v_med3_f32 v73, v61, 0, v201
	v_mul_f32_e32 v66, v70, v6
	v_fma_f32 v66, v71, v7, v66
	v_fma_f32 v66, v72, v8, v66
	v_fma_f32 v66, v73, v9, v66
	v_med3_f32 v70, v62, 0, v201
	v_med3_f32 v71, v63, 0, v201
	v_med3_f32 v72, v64, 0, v201
	v_med3_f32 v73, v65, 0, v201
	v_mul_f32_e32 v67, v70, v2
	v_fma_f32 v67, v71, v3, v67
	v_fma_f32 v67, v72, v4, v67
	v_fma_f32 v67, v73, v5, v67
	s_nop 1
	v_permlane16_swap_b32 v66, v67
	s_nop 0
	v_add_f32_e32 v68, v66, v67
	v_add_f32_e32 v68, 0, v68
	v_ashrrev_i32_e32 v69, 31, v68
	v_or_b32_e32 v69, 0x80000000, v69
	v_xor_b32_e32 v68, v68, v69
	ds_write_b32 v78, v68 offset:256
	v_med3_f32 v70, v86, 0, v201
	v_med3_f32 v71, v87, 0, v201
	v_med3_f32 v72, v88, 0, v201
	v_med3_f32 v73, v89, 0, v201
	v_mul_f32_e32 v66, v70, v6
	v_fma_f32 v66, v71, v7, v66
	v_fma_f32 v66, v72, v8, v66
	v_fma_f32 v66, v73, v9, v66
	v_med3_f32 v70, v90, 0, v201
	v_med3_f32 v71, v91, 0, v201
	v_med3_f32 v72, v92, 0, v201
	v_med3_f32 v73, v93, 0, v201
	v_mul_f32_e32 v67, v70, v2
	v_fma_f32 v67, v71, v3, v67
	v_fma_f32 v67, v72, v4, v67
	v_fma_f32 v67, v73, v5, v67
	s_nop 1
	v_permlane16_swap_b32 v66, v67
	s_nop 0
	v_add_f32_e32 v68, v66, v67
	v_add_f32_e32 v68, 0, v68
	v_ashrrev_i32_e32 v69, 31, v68
	v_or_b32_e32 v69, 0x80000000, v69
	v_xor_b32_e32 v68, v68, v69
	ds_write_b32 v78, v68 offset:512
	v_med3_f32 v70, v94, 0, v201
	v_med3_f32 v71, v95, 0, v201
	v_med3_f32 v72, v96, 0, v201
	v_med3_f32 v73, v97, 0, v201
	v_mul_f32_e32 v66, v70, v6
	v_fma_f32 v66, v71, v7, v66
	v_fma_f32 v66, v72, v8, v66
	v_fma_f32 v66, v73, v9, v66
	v_med3_f32 v70, v98, 0, v201
	v_med3_f32 v71, v99, 0, v201
	v_med3_f32 v72, v100, 0, v201
	v_med3_f32 v73, v101, 0, v201
	v_mul_f32_e32 v67, v70, v2
	v_fma_f32 v67, v71, v3, v67
	v_fma_f32 v67, v72, v4, v67
	v_fma_f32 v67, v73, v5, v67
	s_nop 1
	v_permlane16_swap_b32 v66, v67
	s_nop 0
	v_add_f32_e32 v68, v66, v67
	v_add_f32_e32 v68, 0, v68
	v_ashrrev_i32_e32 v69, 31, v68
	v_or_b32_e32 v69, 0x80000000, v69
	v_xor_b32_e32 v68, v68, v69
	ds_write_b32 v78, v68 offset:768
	v_add_u32_e32 v78, 0x400, v78
	s_add_i32 s9, s9, 1
	s_cmp_ge_u32 s9, s8
	s_cbranch_scc1 .Lidx_done

.Lidx_cY:
	v_mfma_f32_16x16x32_bf16 v[50:53], v[10:13], v[34:37], 0
	v_mfma_f32_16x16x32_bf16 v[54:57], v[14:17], v[34:37], 0
	v_mfma_f32_16x16x32_bf16 v[58:61], v[10:13], v[38:41], 0
	v_mfma_f32_16x16x32_bf16 v[62:65], v[14:17], v[38:41], 0
	v_mfma_f32_16x16x32_bf16 v[86:89], v[10:13], v[42:45], 0
	v_mfma_f32_16x16x32_bf16 v[90:93], v[14:17], v[42:45], 0
	v_mfma_f32_16x16x32_bf16 v[94:97], v[10:13], v[46:49], 0
	v_mfma_f32_16x16x32_bf16 v[98:101], v[14:17], v[46:49], 0
	s_add_i32 s10, s9, 2
	s_cmp_lt_u32 s10, s8
	s_cbranch_scc0 .Lidx_nlY
	global_load_dwordx4 v[34:37], v[74:75], off
	v_lshl_add_u64 v[74:75], v[74:75], 0, s[14:15]
	global_load_dwordx4 v[38:41], v[74:75], off
	v_lshl_add_u64 v[74:75], v[74:75], 0, s[14:15]
	global_load_dwordx4 v[42:45], v[74:75], off
	v_lshl_add_u64 v[74:75], v[74:75], 0, s[14:15]
	global_load_dwordx4 v[46:49], v[74:75], off
	v_lshl_add_u64 v[74:75], v[74:75], 0, s[14:15]
.Lidx_nlY:
	s_nop 1
	v_med3_f32 v70, v50, 0, v201
	v_med3_f32 v71, v51, 0, v201
	v_med3_f32 v72, v52, 0, v201
	v_med3_f32 v73, v53, 0, v201
	v_mul_f32_e32 v66, v70, v6
	v_fma_f32 v66, v71, v7, v66
	v_fma_f32 v66, v72, v8, v66
	v_fma_f32 v66, v73, v9, v66
	v_med3_f32 v70, v54, 0, v201
	v_med3_f32 v71, v55, 0, v201
	v_med3_f32 v72, v56, 0, v201
	v_med3_f32 v73, v57, 0, v201
	v_mul_f32_e32 v67, v70, v2
	v_fma_f32 v67, v71, v3, v67
	v_fma_f32 v67, v72, v4, v67
	v_fma_f32 v67, v73, v5, v67
	s_nop 1
	v_permlane16_swap_b32 v66, v67
	s_nop 0
	v_add_f32_e32 v68, v66, v67
	v_add_f32_e32 v68, 0, v68
	v_ashrrev_i32_e32 v69, 31, v68
	v_or_b32_e32 v69, 0x80000000, v69
	v_xor_b32_e32 v68, v68, v69
	ds_write_b32 v78, v68
	v_med3_f32 v70, v58, 0, v201
	v_med3_f32 v71, v59, 0, v201
	v_med3_f32 v72, v60, 0, v201
	v_med3_f32 v73, v61, 0, v201
	v_mul_f32_e32 v66, v70, v6
	v_fma_f32 v66, v71, v7, v66
	v_fma_f32 v66, v72, v8, v66
	v_fma_f32 v66, v73, v9, v66
	v_med3_f32 v70, v62, 0, v201
	v_med3_f32 v71, v63, 0, v201
	v_med3_f32 v72, v64, 0, v201
	v_med3_f32 v73, v65, 0, v201
	v_mul_f32_e32 v67, v70, v2
	v_fma_f32 v67, v71, v3, v67
	v_fma_f32 v67, v72, v4, v67
	v_fma_f32 v67, v73, v5, v67
	s_nop 1
	v_permlane16_swap_b32 v66, v67
	s_nop 0
	v_add_f32_e32 v68, v66, v67
	v_add_f32_e32 v68, 0, v68
	v_ashrrev_i32_e32 v69, 31, v68
	v_or_b32_e32 v69, 0x80000000, v69
	v_xor_b32_e32 v68, v68, v69
	ds_write_b32 v78, v68 offset:256
	v_med3_f32 v70, v86, 0, v201
	v_med3_f32 v71, v87, 0, v201
	v_med3_f32 v72, v88, 0, v201
	v_med3_f32 v73, v89, 0, v201
	v_mul_f32_e32 v66, v70, v6
	v_fma_f32 v66, v71, v7, v66
	v_fma_f32 v66, v72, v8, v66
	v_fma_f32 v66, v73, v9, v66
	v_med3_f32 v70, v90, 0, v201
	v_med3_f32 v71, v91, 0, v201
	v_med3_f32 v72, v92, 0, v201
	v_med3_f32 v73, v93, 0, v201
	v_mul_f32_e32 v67, v70, v2
	v_fma_f32 v67, v71, v3, v67
	v_fma_f32 v67, v72, v4, v67
	v_fma_f32 v67, v73, v5, v67
	s_nop 1
	v_permlane16_swap_b32 v66, v67
	s_nop 0
	v_add_f32_e32 v68, v66, v67
	v_add_f32_e32 v68, 0, v68
	v_ashrrev_i32_e32 v69, 31, v68
	v_or_b32_e32 v69, 0x80000000, v69
	v_xor_b32_e32 v68, v68, v69
	ds_write_b32 v78, v68 offset:512
	v_med3_f32 v70, v94, 0, v201
	v_med3_f32 v71, v95, 0, v201
	v_med3_f32 v72, v96, 0, v201
	v_med3_f32 v73, v97, 0, v201
	v_mul_f32_e32 v66, v70, v6
	v_fma_f32 v66, v71, v7, v66
	v_fma_f32 v66, v72, v8, v66
	v_fma_f32 v66, v73, v9, v66
	v_med3_f32 v70, v98, 0, v201
	v_med3_f32 v71, v99, 0, v201
	v_med3_f32 v72, v100, 0, v201
	v_med3_f32 v73, v101, 0, v201
	v_mul_f32_e32 v67, v70, v2
	v_fma_f32 v67, v71, v3, v67
	v_fma_f32 v67, v72, v4, v67
	v_fma_f32 v67, v73, v5, v67
	s_nop 1
	v_permlane16_swap_b32 v66, v67
	s_nop 0
	v_add_f32_e32 v68, v66, v67
	v_add_f32_e32 v68, 0, v68
	v_ashrrev_i32_e32 v69, 31, v68
	v_or_b32_e32 v69, 0x80000000, v69
	v_xor_b32_e32 v68, v68, v69
	ds_write_b32 v78, v68 offset:768
	v_add_u32_e32 v78, 0x400, v78
	s_add_i32 s9, s9, 1
	s_cmp_lt_u32 s9, s8
	s_cbranch_scc1 .Lidx_loopX
.Lidx_done:
	s_waitcnt lgkmcnt(0)
	s_barrier
.LBB0_601:
	s_add_i32 s0, s50, 16
	s_and_b32 s30, s0, 0x70
	s_add_i32 s0, s50, 1
	s_cmp_ge_u32 s0, s30
	s_cbranch_scc1 .LBB0_609
	s_not_b32 s1, s50
	s_add_i32 s4, s30, s1
	s_cmp_lt_u32 s4, 2
	s_mov_b64 s[2:3], -1
	s_cbranch_scc1 .LBB0_606
	s_and_b32 s5, s1, 1
	s_add_i32 s2, s5, s50
	s_add_i32 s1, s0, 1
	s_sub_i32 s2, s2, s30
	s_add_i32 s6, s2, 1
	s_mov_b64 s[2:3], s[0:1]
